# v72 = v70 + sb: 37 redundant canonicalising v_max (x,x) before max(0,x) removed (exact), hazard distances re-padded
# speedup vs baseline: 1.0048x; 1.0048x over previous
.LBB0_226:
	s_or_b64 exec, exec, s[12:13]
	s_lshl_b32 s0, s5, 8
	s_and_b32 s0, s0, 0xf00
	ds_read_b128 v[64:67], v221
	ds_read_b128 v[68:71], v221 offset:64
	ds_read_b128 v[76:79], v221 offset:2304
	ds_read_b128 v[80:83], v221 offset:2368
	v_or_b32_e32 v101, v168, v122
	v_or_b32_e32 v116, 3, v101
	v_cmp_lt_u32_e64 s[28:29], v116, v100
	v_or_b32_e32 v102, 16, v100
	v_cmp_lt_u32_e64 s[12:13], v101, v102
	v_cmp_lt_u32_e64 s[14:15], v116, v102
	s_waitcnt lgkmcnt(3)
	v_mfma_f32_16x16x32_bf16 v[72:75], v[64:67], v[48:51], 0
	s_waitcnt lgkmcnt(1)
	v_mfma_f32_16x16x32_bf16 v[84:87], v[76:79], v[48:51], 0
	v_mfma_f32_16x16x32_bf16 v[88:91], v[76:79], v[52:55], 0
	v_mfma_f32_16x16x32_bf16 v[72:75], v[68:71], v[56:59], v[72:75]
	v_mfma_f32_16x16x32_bf16 v[64:67], v[64:67], v[52:55], 0
	s_waitcnt lgkmcnt(0)
	v_mfma_f32_16x16x32_bf16 v[76:79], v[80:83], v[56:59], v[84:87]
	s_nop 4
	v_mul_f32_e64 v92, |v75|, s51
	v_mfma_f32_16x16x32_bf16 v[80:83], v[80:83], v[60:63], v[88:91]
	v_max_f32_e32 v113, 0, v73
	v_max_f32_e32 v84, v72, v72
	s_nop 0
	v_mul_f32_e64 v88, |v73|, s51
	v_mfma_f32_16x16x32_bf16 v[68:71], v[68:71], v[60:63], v[64:67]
	v_exp_f32_e32 v87, v88
	v_max_f32_e32 v104, v76, v76
	v_mul_f32_e64 v110, |v79|, s51
	v_max_f32_e32 v89, v74, v74
	v_add_f32_e32 v87, 1.0, v87
	s_nop 2
	v_max_f32_e32 v97, v70, v70
	v_mul_f32_e64 v90, |v74|, s51
	v_max_f32_e32 v91, v75, v75
	v_max_f32_e32 v93, v68, v68
	v_mul_f32_e64 v94, |v68|, s51
	v_mul_f32_e64 v96, |v69|, s51
	v_mul_f32_e64 v98, |v70|, s51
	v_mul_f32_e64 v107, |v77|, s51
	v_max_f32_e32 v111, 0, v84
	v_max_f32_e32 v84, 0, v97
	v_max_f32_e32 v97, 0, v104
	v_exp_f32_e32 v104, v110
	v_log_f32_e32 v87, v87
	v_mul_f32_e64 v105, |v76|, s51
	v_max_f32_e32 v114, 0, v89
	v_exp_f32_e32 v89, v90
	v_max_f32_e32 v115, 0, v91
	v_exp_f32_e32 v90, v92
	v_max_f32_e32 v92, 0, v93
	v_exp_f32_e32 v91, v94
	v_exp_f32_e32 v93, v96
	v_exp_f32_e32 v94, v98
	v_exp_f32_e32 v98, v107
	v_exp_f32_e32 v96, v105
	v_fmac_f32_e32 v113, 0x3f317218, v87
	v_add_f32_e32 v87, 1.0, v104
	v_mul_f32_e64 v103, |v71|, s51
	v_add_f32_e32 v93, 1.0, v93
	v_add_f32_e32 v107, 1.0, v98
	v_log_f32_e32 v87, v87
	v_or_b32_e32 v85, 16, v101
	v_max_f32_e32 v88, 0, v69
	v_exp_f32_e32 v95, v103
	v_max_f32_e32 v103, 0, v77
	v_add_f32_e32 v106, 1.0, v96
	v_log_f32_e32 v96, v93
	v_log_f32_e32 v93, v107
	v_cmp_lt_u32_e32 vcc, v85, v100
	v_mul_f32_e64 v86, |v72|, s51
	v_mul_f32_e64 v109, |v78|, s51
	v_max_f32_e32 v104, 0, v79
	v_mul_f32_e64 v85, |v80|, s51
	v_exp_f32_e32 v112, v86
	v_max_f32_e32 v86, 0, v71
	v_exp_f32_e32 v99, v109
	v_exp_f32_e32 v85, v85
	v_fmac_f32_e32 v104, 0x3f317218, v87
	v_add_f32_e32 v89, 1.0, v89
	v_fmac_f32_e32 v103, 0x3f317218, v93
	v_max_f32_e32 v93, 0, v80
	v_mul_f32_e64 v87, |v81|, s51
	v_add_f32_e32 v91, 1.0, v91
	v_log_f32_e32 v89, v89
	v_exp_f32_e32 v87, v87
	v_log_f32_e32 v98, v91
	v_log_f32_e32 v91, v106
	v_add_f32_e32 v90, 1.0, v90
	v_add_f32_e32 v94, 1.0, v94
	v_add_f32_e32 v95, 1.0, v95
	v_add_f32_e32 v99, 1.0, v99
	v_add_f32_e32 v85, 1.0, v85
	v_log_f32_e32 v109, v90
	v_log_f32_e32 v90, v94
	v_log_f32_e32 v94, v95
	v_log_f32_e32 v95, v99
	v_log_f32_e32 v99, v85
	v_fmac_f32_e32 v114, 0x3f317218, v89
	v_max_f32_e32 v89, 0, v81
	v_add_f32_e32 v85, 1.0, v87
	v_mul_f32_e64 v87, |v82|, s51
	v_fmac_f32_e32 v97, 0x3f317218, v91
	v_exp_f32_e32 v91, v87
	v_cndmask_b32_e64 v106, 0, -v97, vcc
	v_log_f32_e32 v97, v85
	v_add_f32_e32 v105, 1.0, v112
	v_max_f32_e32 v87, 0, v82
	v_add_f32_e32 v85, 1.0, v91
	v_mul_f32_e64 v91, |v83|, s51
	v_log_f32_e32 v105, v105
	v_exp_f32_e32 v91, v91
	v_fmac_f32_e32 v115, 0x3f317218, v109
	v_or_b32_e32 v109, 1, v101
	v_or_b32_e32 v112, 2, v101
	v_fmac_f32_e32 v111, 0x3f317218, v105
	v_max_f32_e32 v107, 0, v78
	v_add_f32_e32 v91, 1.0, v91
	v_cmp_lt_u32_e64 s[36:37], v109, v100
	v_cmp_lt_u32_e64 s[26:27], v112, v100
	v_cndmask_b32_e64 v105, 0, -v111, s[10:11]
	v_fmac_f32_e32 v107, 0x3f317218, v95
	v_log_f32_e32 v95, v85
	v_log_f32_e32 v91, v91
	v_cndmask_b32_e64 v110, 0, -v113, s[36:37]
	v_or_b32_e32 v111, 19, v101
	v_cndmask_b32_e64 v113, 0, -v114, s[26:27]
	v_or_b32_e32 v114, 18, v101
	v_or_b32_e32 v108, 17, v101
	v_cmp_lt_u32_e64 s[30:31], v114, v100
	v_cmp_lt_u32_e64 s[34:35], v111, v100
	v_cndmask_b32_e64 v115, 0, -v115, s[28:29]
	v_cmp_lt_u32_e64 s[38:39], v108, v100
	v_cndmask_b32_e64 v107, 0, -v107, s[30:31]
	v_cndmask_b32_e64 v100, 0, -v104, s[34:35]
	v_max_f32_e32 v85, 0, v83
	v_cndmask_b32_e64 v103, 0, -v103, s[38:39]
	v_pk_fma_f32 v[92:93], v[98:99], s[62:63], v[92:93] op_sel_hi:[1,0,1]
	v_cmp_lt_u32_e64 s[18:19], v108, v102
	v_cmp_lt_u32_e64 s[20:21], v109, v102
	v_cmp_lt_u32_e64 s[16:17], v114, v102
	v_cmp_lt_u32_e64 s[22:23], v111, v102
	v_cmp_lt_u32_e64 s[24:25], v112, v102
	v_add_f32_e32 v98, v115, v113
	v_add_f32_e32 v102, v100, v107
	v_pk_fma_f32 v[86:87], v[94:95], s[62:63], v[86:87] op_sel_hi:[1,0,1]
	v_pk_fma_f32 v[84:85], v[90:91], s[62:63], v[84:85] op_sel_hi:[1,0,1]
	v_add_f32_e32 v99, v110, v98
	v_add_f32_e32 v103, v103, v102
	v_pk_fma_f32 v[88:89], v[96:97], s[62:63], v[88:89] op_sel_hi:[1,0,1]
	v_cndmask_b32_e64 v87, 0, -v87, s[16:17]
	v_cndmask_b32_e64 v86, 0, -v86, s[14:15]
	v_cndmask_b32_e64 v85, 0, -v85, s[22:23]
	v_cndmask_b32_e64 v84, 0, -v84, s[24:25]
	v_add_f32_e32 v101, v105, v99
	v_add_f32_e32 v105, v106, v103
	v_cndmask_b32_e64 v89, 0, -v89, s[18:19]
	v_cndmask_b32_e64 v88, 0, -v88, s[20:21]
	v_pk_add_f32 v[90:91], v[84:85], v[86:87]
	v_mov_b32_e32 v84, v101
	v_mov_b32_e32 v87, v101
	v_mov_b32_e32 v94, v105
	v_mov_b32_e32 v95, v105
	v_cndmask_b32_e64 v93, 0, -v93, s[10:11]
	v_cndmask_b32_e64 v92, 0, -v92, s[12:13]
	v_pk_add_f32 v[88:89], v[88:89], v[90:91]
	v_permlane16_swap_b32_e32 v84, v87
	v_permlane16_swap_b32_e32 v94, v95
	v_pk_add_f32 v[92:93], v[92:93], v[88:89]
	v_cndmask_b32_e64 v84, v84, v87, s[8:9]
	v_cndmask_b32_e64 v94, v94, v95, s[8:9]
	v_add_f32_e32 v108, v101, v84
	v_mov_b32_e32 v84, v92
	v_mov_b32_e32 v87, v92
	v_add_f32_e32 v106, v105, v94
	v_mov_b32_e32 v94, v93
	v_mov_b32_e32 v95, v93
	v_permlane16_swap_b32_e32 v84, v87
	s_nop 0
	v_permlane16_swap_b32_e32 v94, v95
	v_cndmask_b32_e64 v95, v94, v95, s[8:9]
	v_cndmask_b32_e64 v94, v84, v87, s[8:9]
	v_mov_b32_e32 v84, v108
	v_mov_b32_e32 v87, v108
	v_mov_b32_e32 v96, v106
	v_mov_b32_e32 v97, v106
	v_pk_add_f32 v[94:95], v[92:93], v[94:95]
	v_permlane32_swap_b32_e32 v84, v87
	v_permlane32_swap_b32_e32 v96, v97
	v_cndmask_b32_e64 v109, v84, v87, s[6:7]
	v_mov_b32_e32 v84, v94
	v_mov_b32_e32 v87, v94
	v_cndmask_b32_e64 v107, v96, v97, s[6:7]
	v_mov_b32_e32 v96, v95
	v_mov_b32_e32 v97, v95
	v_permlane32_swap_b32_e32 v84, v87
	s_nop 0
	v_permlane32_swap_b32_e32 v96, v97
	v_add_f32_e32 v104, v106, v107
	v_cndmask_b32_e64 v97, v96, v97, s[6:7]
	v_cndmask_b32_e64 v96, v84, v87, s[6:7]
	v_sub_f32_e32 v84, v106, v105
	v_add_f32_e32 v87, 0, v104
	v_sub_f32_e32 v106, v108, v101
	v_fmac_f32_e32 v87, v208, v106
	v_fmac_f32_e32 v87, v209, v109
	v_add_f32_e32 v72, v72, v87
	v_add_f32_e32 v73, v73, v87
	v_add_f32_e32 v72, v101, v72
	v_add_f32_e32 v73, v99, v73
	v_mul_f32_e32 v72, 0x3fb8aa3b, v72
	v_mul_f32_e32 v73, 0x3fb8aa3b, v73
	v_exp_f32_e32 v72, v72
	v_exp_f32_e32 v73, v73
	v_fma_f32 v84, v208, v84, 0
	v_fmac_f32_e32 v84, v209, v107
	v_cndmask_b32_e64 v99, 0, v72, s[10:11]
	v_cndmask_b32_e64 v101, 0, v73, s[36:37]
	v_add_f32_e32 v72, v78, v84
	v_add_f32_e32 v73, v74, v87
	v_add_f32_e32 v72, v102, v72
	v_add_f32_e32 v73, v98, v73
	v_mul_f32_e32 v72, 0x3fb8aa3b, v72
	v_mul_f32_e32 v73, 0x3fb8aa3b, v73
	v_exp_f32_e32 v72, v72
	v_exp_f32_e32 v73, v73
	v_add_f32_e32 v74, v79, v84
	v_pk_add_f32 v[106:107], v[94:95], v[96:97]
	v_cndmask_b32_e64 v78, 0, v72, s[30:31]
	v_cndmask_b32_e64 v79, 0, v73, s[26:27]
	v_pk_add_f32 v[72:73], v[94:95], v[92:93] neg_lo:[0,1] neg_hi:[0,1]
	v_add_f32_e32 v76, v76, v84
	v_fma_f32 v73, v208, v73, 0
	v_add_f32_e32 v77, v77, v84
	v_fmac_f32_e32 v73, v209, v97
	v_add_f32_e32 v84, 0, v107
	v_fmac_f32_e32 v84, v208, v72
	v_add_f32_e32 v72, v80, v73
	v_add_f32_e32 v80, v81, v73
	v_add_f32_e32 v80, v89, v80
	v_mul_f32_e32 v80, 0x3fb8aa3b, v80
	v_exp_f32_e32 v80, v80
	v_fmac_f32_e32 v84, v209, v96
	ds_read2_b64 v[64:67], v222 offset0:32 offset1:36
	v_add_f32_e32 v75, v75, v87
	v_add_f32_e32 v68, v68, v84
	v_add_f32_e32 v69, v69, v84
	v_cndmask_b32_e64 v87, 0, v80, s[18:19]
	v_add_f32_e32 v80, v82, v73
	v_add_f32_e32 v70, v70, v84
	v_add_f32_e32 v73, v83, v73
	v_add_f32_e32 v71, v71, v84
	v_add_f32_e32 v76, v105, v76
	v_add_f32_e32 v77, v103, v77
	v_add_f32_e32 v74, v100, v74
	v_add_f32_e32 v75, v115, v75
	v_add_f32_e32 v72, v93, v72
	v_add_f32_e32 v68, v92, v68
	v_add_f32_e32 v69, v88, v69
	v_add_f32_e32 v80, v91, v80
	v_add_f32_e32 v70, v90, v70
	v_add_f32_e32 v73, v85, v73
	v_add_f32_e32 v71, v86, v71
	v_mul_f32_e32 v76, 0x3fb8aa3b, v76
	v_mul_f32_e32 v77, 0x3fb8aa3b, v77
	v_mul_f32_e32 v74, 0x3fb8aa3b, v74
	v_mul_f32_e32 v75, 0x3fb8aa3b, v75
	v_mul_f32_e32 v72, 0x3fb8aa3b, v72
	v_mul_f32_e32 v68, 0x3fb8aa3b, v68
	v_mul_f32_e32 v69, 0x3fb8aa3b, v69
	v_mul_f32_e32 v80, 0x3fb8aa3b, v80
	v_mul_f32_e32 v70, 0x3fb8aa3b, v70
	v_mul_f32_e32 v73, 0x3fb8aa3b, v73
	v_mul_f32_e32 v71, 0x3fb8aa3b, v71
	v_exp_f32_e32 v76, v76
	v_exp_f32_e32 v77, v77
	v_exp_f32_e32 v74, v74
	v_exp_f32_e32 v75, v75
	v_exp_f32_e32 v72, v72
	v_exp_f32_e32 v68, v68
	v_exp_f32_e32 v69, v69
	v_exp_f32_e32 v80, v80
	v_exp_f32_e32 v70, v70
	v_exp_f32_e32 v73, v73
	v_exp_f32_e32 v71, v71
	v_cndmask_b32_e32 v76, 0, v76, vcc
	v_cndmask_b32_e64 v77, 0, v77, s[38:39]
	v_cndmask_b32_e64 v74, 0, v74, s[34:35]
	v_cndmask_b32_e64 v75, 0, v75, s[28:29]
	v_cndmask_b32_e64 v72, 0, v72, s[10:11]
	v_cndmask_b32_e64 v68, 0, v68, s[12:13]
	v_cndmask_b32_e64 v69, 0, v69, s[20:21]
	v_cndmask_b32_e64 v84, 0, v80, s[16:17]
	v_cndmask_b32_e64 v70, 0, v70, s[24:25]
	v_cndmask_b32_e64 v73, 0, v73, s[22:23]
	v_cndmask_b32_e64 v71, 0, v71, s[14:15]
	v_cvt_pk_bf16_f32 v80, v99, v101
	v_cvt_pk_bf16_f32 v81, v79, v75
	v_cvt_pk_bf16_f32 v82, v76, v77
	v_cvt_pk_bf16_f32 v83, v78, v74
	v_cvt_pk_bf16_f32 v96, v68, v69
	v_cvt_pk_bf16_f32 v97, v70, v71
	v_cvt_pk_bf16_f32 v98, v72, v87
	v_cvt_pk_bf16_f32 v99, v84, v73
	s_waitcnt lgkmcnt(0)
	v_mfma_f32_16x16x32_bf16 v[92:95], v[64:67], v[80:83], 0
	ds_read2_b64 v[100:103], v212 offset1:4
	s_add_i32 s14, s0, 0xffffff80
	s_cmp_eq_u32 s0, 0
	v_mfma_f32_16x16x32_bf16 v[76:79], v[64:67], v[96:99], 0
	ds_read2_b64 v[64:67], v210 offset1:4
	s_cselect_b64 s[12:13], -1, 0
	v_mov_b32_e32 v105, v107
	s_waitcnt lgkmcnt(0)
	v_mfma_f32_16x16x32_bf16 v[88:91], v[64:67], v[80:83], 0
	s_and_b64 s[0:1], s[12:13], exec
	s_cselect_b32 s22, 0, s14
	v_mfma_f32_16x16x32_bf16 v[72:75], v[64:67], v[96:99], 0
	ds_read2_b64 v[64:67], v211 offset1:4
	s_waitcnt lgkmcnt(0)
	v_mfma_f32_16x16x32_bf16 v[84:87], v[64:67], v[80:83], 0
	v_mfma_f32_16x16x32_bf16 v[68:71], v[64:67], v[96:99], 0
	v_add_f32_e32 v64, v108, v109
	v_mov_b32_e32 v65, v106
	v_pk_add_f32 v[104:105], v[64:65], v[104:105]
	v_mfma_f32_16x16x32_bf16 v[80:83], v[100:103], v[80:83], 0
	v_cmp_gt_f32_e32 vcc, s63, v104
	v_cmp_gt_f32_e64 s[0:1], s63, v105
	s_and_b64 s[0:1], vcc, s[0:1]
	v_mfma_f32_16x16x32_bf16 v[64:67], v[100:103], v[96:99], 0
	v_cndmask_b32_e64 v96, 0, 1, s[0:1]
	v_cmp_ne_u32_e32 vcc, 0, v96
	v_pk_add_f32 v[170:171], v[104:105], 0 op_sel_hi:[1,0]
	s_cmp_eq_u64 vcc, exec
	s_mov_b64 s[0:1], -1
	s_cbranch_scc1 .LBB0_232
	v_cmp_lt_i32_e32 vcc, s22, v168
	s_mov_b64 s[0:1], 0
	s_and_saveexec_b64 s[14:15], vcc
	s_cbranch_execz .LBB0_231
	s_and_b32 s0, s33, 0xf00
	v_add_u32_e32 v112, s0, v213
	s_mov_b64 s[16:17], 0
	v_mov_b32_e32 v113, v214
	v_mov_b32_e32 v114, v125
.LBB0_229:
	v_add_u32_e32 v96, 0, v113
	ds_read_b128 v[116:119], v96
	ds_read_b128 v[172:175], v96 offset:64
	ds_read_b128 v[224:227], v96 offset:2304
	ds_read_b128 v[228:231], v96 offset:2368
	v_add_u32_e32 v110, 0, v114
	s_waitcnt lgkmcnt(3)
	v_mfma_f32_16x16x32_bf16 v[232:235], v[116:119], v[48:51], 0
	v_add_u32_e32 v96, 0xd800, v110
	ds_read2_b64 v[100:103], v96 offset0:24 offset1:28
	v_add_u32_e32 v96, 0x109c0, v110
	s_waitcnt lgkmcnt(3)
	v_mfma_f32_16x16x32_bf16 v[232:235], v[172:175], v[56:59], v[232:235]
	v_add_u32_e32 v98, 0x109e0, v110
	ds_read_b64 v[96:97], v96
	ds_read_b64 v[98:99], v98
	v_mfma_f32_16x16x32_bf16 v[116:119], v[116:119], v[52:55], 0
	v_add_u32_e32 v104, 0x13ac0, v110
	s_nop 2
	v_mul_f32_e64 v132, |v232|, s51
	v_exp_f32_e32 v132, v132
	v_mul_f32_e64 v141, |v233|, s51
	v_exp_f32_e32 v141, v141
	v_mul_f32_e64 v143, |v234|, s51
	v_add_f32_e32 v132, 1.0, v132
	v_exp_f32_e32 v143, v143
	v_log_f32_e32 v132, v132
	v_mul_f32_e64 v149, |v235|, s51
	v_add_f32_e32 v141, 1.0, v141
	v_exp_f32_e32 v149, v149
	v_log_f32_e32 v141, v141
	v_max_f32_e32 v115, 0, v232
	v_add_f32_e32 v143, 1.0, v143
	v_fmac_f32_e32 v115, 0x3f317218, v132
	v_log_f32_e32 v143, v143
	v_max_f32_e32 v132, 0, v233
	v_add_f32_e32 v149, 1.0, v149
	v_mfma_f32_16x16x32_bf16 v[116:119], v[172:175], v[60:63], v[116:119]
	v_fmac_f32_e32 v132, 0x3f317218, v141
	v_log_f32_e32 v149, v149
	v_max_f32_e32 v141, 0, v234
	v_fmac_f32_e32 v141, 0x3f317218, v143
	v_max_f32_e32 v143, 0, v235
	v_fmac_f32_e32 v143, 0x3f317218, v149
	s_nop 1
	v_max_f32_e32 v176, 0, v116
	v_mul_f32_e64 v149, |v116|, s51
	v_exp_f32_e32 v149, v149
	s_waitcnt lgkmcnt(4)
	v_mfma_f32_16x16x32_bf16 v[236:239], v[224:227], v[48:51], 0
	v_sub_f32_e64 v141, -v141, v143
	v_sub_f32_e32 v132, v141, v132
	v_add_f32_e32 v149, 1.0, v149
	v_mfma_f32_16x16x32_bf16 v[224:227], v[224:227], v[52:55], 0
	v_sub_f32_e32 v115, v132, v115
	v_mov_b32_e32 v159, v115
	v_add_u32_e32 v106, 0x13ae0, v110
	s_waitcnt lgkmcnt(3)
	v_mfma_f32_16x16x32_bf16 v[172:175], v[228:231], v[56:59], v[236:239]
	v_add_u32_e32 v108, 0x16bc0, v110
	v_add_u32_e32 v110, 0x16be0, v110
	ds_read_b64 v[104:105], v104
	ds_read_b64 v[106:107], v106
	v_mfma_f32_16x16x32_bf16 v[224:227], v[228:231], v[60:63], v[224:227]
	v_log_f32_e32 v228, v149
	v_max_f32_e32 v230, 0, v117
	v_mul_f32_e64 v149, |v117|, s51
	v_exp_f32_e32 v149, v149
	v_mul_f32_e64 v151, |v172|, s51
	v_exp_f32_e32 v151, v151
	v_mul_f32_e64 v153, |v173|, s51
	v_add_f32_e32 v149, 1.0, v149
	v_log_f32_e32 v236, v149
	v_max_f32_e32 v238, 0, v118
	v_mul_f32_e64 v149, |v118|, s51
	v_exp_f32_e32 v149, v149
	v_exp_f32_e32 v153, v153
	v_mul_f32_e64 v155, |v174|, s51
	v_add_f32_e32 v151, 1.0, v151
	v_add_f32_e32 v149, 1.0, v149
	v_log_f32_e32 v240, v149
	v_max_f32_e32 v242, 0, v119
	v_mul_f32_e64 v149, |v119|, s51
	v_exp_f32_e32 v149, v149
	v_exp_f32_e32 v155, v155
	v_log_f32_e32 v151, v151
	v_mul_f32_e64 v157, |v175|, s51
	v_add_f32_e32 v149, 1.0, v149
	v_add_f32_e32 v153, 1.0, v153
	v_exp_f32_e32 v157, v157
	v_log_f32_e32 v244, v149
	v_log_f32_e32 v153, v153
	v_max_f32_e32 v149, 0, v172
	v_add_f32_e32 v155, 1.0, v155
	v_fmac_f32_e32 v149, 0x3f317218, v151
	v_log_f32_e32 v155, v155
	v_max_f32_e32 v151, 0, v173
	v_add_f32_e32 v157, 1.0, v157
	v_fmac_f32_e32 v151, 0x3f317218, v153
	v_log_f32_e32 v157, v157
	v_max_f32_e32 v153, 0, v174
	v_fmac_f32_e32 v153, 0x3f317218, v155
	v_max_f32_e32 v155, 0, v175
	v_fmac_f32_e32 v155, 0x3f317218, v157
	v_max_f32_e32 v177, 0, v224
	v_mul_f32_e64 v157, |v224|, s51
	v_exp_f32_e32 v157, v157
	v_sub_f32_e64 v153, -v153, v155
	v_sub_f32_e32 v151, v153, v151
	v_sub_f32_e32 v149, v151, v149
	v_add_f32_e32 v157, 1.0, v157
	v_log_f32_e32 v229, v157
	v_max_f32_e32 v231, 0, v225
	v_mul_f32_e64 v157, |v225|, s51
	v_exp_f32_e32 v157, v157
	v_mov_b32_e32 v161, v149
	ds_read_b64 v[108:109], v108
	ds_read_b64 v[110:111], v110
	v_add_f32_e32 v157, 1.0, v157
	v_log_f32_e32 v237, v157
	v_max_f32_e32 v239, 0, v226
	v_mul_f32_e64 v157, |v226|, s51
	v_exp_f32_e32 v157, v157
	v_subrev_u32_e32 v114, 64, v114
	v_add_u32_e32 v113, 0xffffee00, v113
	v_add_f32_e32 v157, 1.0, v157
	v_log_f32_e32 v241, v157
	v_max_f32_e32 v243, 0, v227
	v_mul_f32_e64 v157, |v227|, s51
	v_exp_f32_e32 v157, v157
	s_nop 0
	v_add_f32_e32 v157, 1.0, v157
	v_log_f32_e32 v245, v157
	v_mov_b32_e32 v157, v115
	s_nop 1
	v_permlane16_swap_b32_e32 v157, v159
	v_cndmask_b32_e64 v157, v157, v159, s[8:9]
	v_mov_b32_e32 v159, v149
	v_add_f32_e32 v157, v115, v157
	s_nop 0
	v_permlane16_swap_b32_e32 v159, v161
	v_cndmask_b32_e64 v159, v159, v161, s[8:9]
	v_mov_b32_e32 v161, v157
	v_mov_b32_e32 v163, v157
	v_add_f32_e32 v159, v149, v159
	s_nop 0
	v_permlane32_swap_b32_e32 v161, v163
	v_cndmask_b32_e64 v161, v161, v163, s[6:7]
	v_mov_b32_e32 v163, v159
	v_mov_b32_e32 v165, v159
	s_nop 1
	v_permlane32_swap_b32_e32 v163, v165
	v_cndmask_b32_e64 v163, v163, v165, s[6:7]
	v_add_f32_e32 v246, v159, v163
	v_sub_f32_e32 v159, v159, v149
	v_fma_f32 v159, v208, v159, v170
	v_fmac_f32_e32 v159, v209, v163
	v_add_f32_e32 v163, v170, v246
	v_sub_f32_e32 v165, v157, v115
	v_fmac_f32_e32 v163, v208, v165
	v_fmac_f32_e32 v163, v209, v161
	v_add_f32_e32 v165, v172, v159
	v_add_f32_e32 v149, v149, v165
	v_add_f32_e32 v165, v232, v163
	v_add_f32_e32 v115, v115, v165
	v_add_f32_e32 v165, v173, v159
	v_add_f32_e32 v151, v151, v165
	v_add_f32_e32 v165, v233, v163
	v_add_f32_e32 v132, v132, v165
	v_add_f32_e32 v165, v174, v159
	v_add_f32_e32 v159, v175, v159
	v_pk_fma_f32 v[174:175], v[228:229], s[62:63], v[176:177] op_sel_hi:[1,0,1]
	v_pk_fma_f32 v[176:177], v[236:237], s[62:63], v[230:231] op_sel_hi:[1,0,1]
	v_pk_fma_f32 v[228:229], v[240:241], s[62:63], v[238:239] op_sel_hi:[1,0,1]
	v_pk_fma_f32 v[230:231], v[244:245], s[62:63], v[242:243] op_sel_hi:[1,0,1]
	v_sub_f32_e32 v155, v159, v155
	v_pk_add_f32 v[228:229], v[228:229], v[230:231] neg_lo:[1,1] neg_hi:[1,1]
	v_add_f32_e32 v159, v235, v163
	v_pk_add_f32 v[176:177], v[228:229], v[176:177] neg_lo:[0,1] neg_hi:[0,1]
	v_add_f32_e32 v153, v153, v165
	v_pk_add_f32 v[174:175], v[176:177], v[174:175] neg_lo:[0,1] neg_hi:[0,1]
	v_add_f32_e32 v165, v234, v163
	v_sub_f32_e32 v143, v159, v143
	v_add_f32_e32 v172, v157, v161
	v_mov_b32_e32 v157, v174
	v_mov_b32_e32 v159, v174
	v_mov_b32_e32 v161, v175
	v_mov_b32_e32 v163, v175
	v_permlane16_swap_b32_e32 v157, v159
	s_nop 0
	v_permlane16_swap_b32_e32 v161, v163
	v_cndmask_b32_e64 v233, v161, v163, s[8:9]
	v_cndmask_b32_e64 v232, v157, v159, s[8:9]
	v_pk_add_f32 v[232:233], v[174:175], v[232:233]
	v_add_f32_e32 v141, v141, v165
	v_mov_b32_e32 v157, v232
	v_mov_b32_e32 v159, v232
	v_mov_b32_e32 v161, v233
	v_mov_b32_e32 v163, v233
	v_permlane32_swap_b32_e32 v157, v159
	s_nop 0
	v_permlane32_swap_b32_e32 v161, v163
	v_cndmask_b32_e64 v235, v161, v163, s[6:7]
	v_cndmask_b32_e64 v234, v157, v159, s[6:7]
	v_pk_add_f32 v[236:237], v[232:233], v[174:175] neg_lo:[0,1] neg_hi:[0,1]
	v_pk_add_f32 v[232:233], v[232:233], v[234:235]
	v_fma_f32 v157, v208, v237, v171
	v_add_f32_e32 v159, v171, v233
	v_fmac_f32_e32 v159, v208, v236
	v_fmac_f32_e32 v159, v209, v234
	v_add_f32_e32 v116, v116, v159
	v_add_f32_e32 v116, v174, v116
	v_fmac_f32_e32 v157, v209, v235
	v_mul_f32_e32 v116, 0x3fb8aa3b, v116
	v_exp_f32_e32 v163, v116
	v_add_f32_e32 v116, v225, v157
	v_add_f32_e32 v116, v177, v116
	v_mul_f32_e32 v116, 0x3fb8aa3b, v116
	v_exp_f32_e32 v165, v116
	v_add_f32_e32 v116, v117, v159
	v_add_f32_e32 v116, v176, v116
	v_mul_f32_e32 v116, 0x3fb8aa3b, v116
	v_exp_f32_e32 v167, v116
	v_add_f32_e32 v116, v226, v157
	v_add_f32_e32 v116, v229, v116
	v_mul_f32_e32 v116, 0x3fb8aa3b, v116
	v_exp_f32_e32 v169, v116
	v_add_f32_e32 v116, v118, v159
	v_add_f32_e32 v116, v228, v116
	v_mul_f32_e32 v116, 0x3fb8aa3b, v116
	v_exp_f32_e32 v174, v116
	v_add_f32_e32 v116, v227, v157
	v_sub_f32_e32 v116, v116, v231
	v_mul_f32_e32 v116, 0x3fb8aa3b, v116
	v_add_f32_e32 v161, v224, v157
	v_exp_f32_e32 v157, v116
	v_add_f32_e32 v116, v119, v159
	v_add_f32_e32 v161, v175, v161
	v_sub_f32_e32 v116, v116, v230
	v_mul_f32_e32 v149, 0x3fb8aa3b, v149
	v_mul_f32_e32 v115, 0x3fb8aa3b, v115
	v_mul_f32_e32 v151, 0x3fb8aa3b, v151
	v_mul_f32_e32 v132, 0x3fb8aa3b, v132
	v_mul_f32_e32 v153, 0x3fb8aa3b, v153
	v_mul_f32_e32 v141, 0x3fb8aa3b, v141
	v_mul_f32_e32 v155, 0x3fb8aa3b, v155
	v_mul_f32_e32 v143, 0x3fb8aa3b, v143
	v_mul_f32_e32 v161, 0x3fb8aa3b, v161
	v_mul_f32_e32 v116, 0x3fb8aa3b, v116
	v_exp_f32_e32 v149, v149
	v_exp_f32_e32 v115, v115
	v_exp_f32_e32 v151, v151
	v_exp_f32_e32 v132, v132
	v_exp_f32_e32 v153, v153
	v_exp_f32_e32 v141, v141
	v_exp_f32_e32 v155, v155
	v_exp_f32_e32 v143, v143
	v_exp_f32_e32 v161, v161
	v_exp_f32_e32 v159, v116
	v_mov_b32_e32 v173, v232
	v_mov_b32_e32 v247, v233
	v_pk_add_f32 v[116:117], v[172:173], v[246:247]
	v_cvt_pk_bf16_f32 v118, v149, v151
	v_pk_add_f32 v[170:171], v[170:171], v[116:117]
	v_cvt_pk_bf16_f32 v116, v115, v132
	v_cmp_gt_f32_e32 vcc, s63, v170
	v_cmp_gt_f32_e64 s[0:1], s63, v171
	v_cvt_pk_bf16_f32 v117, v141, v143
	v_cvt_pk_bf16_f32 v119, v153, v155
	v_cvt_pk_bf16_f32 v172, v163, v167
	v_cvt_pk_bf16_f32 v173, v174, v159
	v_cvt_pk_bf16_f32 v174, v161, v165
	v_cvt_pk_bf16_f32 v175, v169, v157
	s_and_b64 s[0:1], vcc, s[0:1]
	s_waitcnt lgkmcnt(4)
	v_mfma_f32_16x16x32_bf16 v[88:91], v[96:99], v[116:119], v[88:91]
	v_mfma_f32_16x16x32_bf16 v[72:75], v[96:99], v[172:175], v[72:75]
	v_cndmask_b32_e64 v96, 0, 1, s[0:1]
	v_cmp_ne_u32_e32 vcc, 0, v96
	s_cmp_eq_u64 vcc, exec
	s_cselect_b64 s[0:1], -1, 0
	v_cmp_ge_i32_e32 vcc, s22, v112
	s_or_b64 s[20:21], s[0:1], vcc
	v_mfma_f32_16x16x32_bf16 v[92:95], v[100:103], v[116:119], v[92:95]
	s_and_b64 s[20:21], exec, s[20:21]
	s_or_b64 s[16:17], s[20:21], s[16:17]
	s_andn2_b64 s[18:19], s[18:19], exec
	v_mfma_f32_16x16x32_bf16 v[76:79], v[100:103], v[172:175], v[76:79]
	s_and_b64 s[0:1], s[0:1], exec
	v_subrev_u32_e32 v112, 32, v112
	s_or_b64 s[18:19], s[18:19], s[0:1]
	s_waitcnt lgkmcnt(2)
	v_mfma_f32_16x16x32_bf16 v[84:87], v[104:107], v[116:119], v[84:87]
	v_mfma_f32_16x16x32_bf16 v[68:71], v[104:107], v[172:175], v[68:71]
	s_waitcnt lgkmcnt(0)
	v_mfma_f32_16x16x32_bf16 v[80:83], v[108:111], v[116:119], v[80:83]
	v_mfma_f32_16x16x32_bf16 v[64:67], v[108:111], v[172:175], v[64:67]
	s_andn2_b64 exec, exec, s[16:17]
	s_cbranch_execnz .LBB0_229
	s_or_b64 exec, exec, s[16:17]
	s_and_b64 s[0:1], s[18:19], exec

.LBB0_234:
	v_add_u32_e32 v132, s54, v146
	v_lshlrev_b64 v[96:97], 7, v[132:133]
	v_add_u32_e32 v132, 16, v132
	v_lshl_add_u64 v[100:101], v[172:173], 0, v[96:97]
	v_lshlrev_b64 v[104:105], 7, v[132:133]
	global_load_dwordx4 v[96:99], v[100:101], off
	v_lshl_add_u64 v[112:113], v[172:173], 0, v[104:105]
	global_load_dwordx4 v[108:111], v[112:113], off
	global_load_dwordx4 v[224:227], v[112:113], off offset:64
	v_lshl_add_u64 v[176:177], s[54:55], 1, v[174:175]
	global_load_dwordx4 v[100:103], v[100:101], off offset:64
	v_lshlrev_b32_e32 v132, 1, v122
	v_lshl_add_u64 v[176:177], v[176:177], 0, v[132:133]
	s_mov_b32 s0, 0x20000
	s_waitcnt vmcnt(3)
	v_mfma_f32_16x16x32_bf16 v[104:107], v[96:99], v[48:51], 0
	v_mfma_f32_16x16x32_bf16 v[96:99], v[96:99], v[52:55], 0
	s_waitcnt vmcnt(2)
	v_mfma_f32_16x16x32_bf16 v[116:119], v[108:111], v[48:51], 0
	s_waitcnt vmcnt(0)
	v_mfma_f32_16x16x32_bf16 v[112:115], v[100:103], v[56:59], v[104:107]
	v_mfma_f32_16x16x32_bf16 v[104:107], v[100:103], v[60:63], v[96:99]
	v_mfma_f32_16x16x32_bf16 v[108:111], v[108:111], v[52:55], 0
	s_nop 5
	v_max_f32_e32 v132, v112, v112
	v_mul_f32_e64 v141, |v112|, s51
	v_max_f32_e32 v143, v113, v113
	v_mfma_f32_16x16x32_bf16 v[116:119], v[224:227], v[56:59], v[116:119]
	v_mul_f32_e64 v149, |v113|, s51
	v_max_f32_e32 v151, v114, v114
	v_mul_f32_e64 v153, |v114|, s51
	v_max_f32_e32 v159, v104, v104
	v_mul_f32_e64 v161, |v104|, s51
	v_mul_f32_e64 v165, |v105|, s51
	v_mfma_f32_16x16x32_bf16 v[108:111], v[224:227], v[60:63], v[108:111]
	v_max_f32_e32 v224, 0, v132
	v_exp_f32_e32 v132, v141
	v_max_f32_e32 v226, 0, v143
	v_exp_f32_e32 v141, v149
	v_max_f32_e32 v228, 0, v151
	v_exp_f32_e32 v143, v153
	v_max_f32_e32 v225, 0, v159
	v_exp_f32_e32 v151, v161
	v_exp_f32_e32 v153, v165
	v_mul_f32_e64 v161, |v116|, s51
	v_mul_f32_e64 v165, |v117|, s51
	v_max_f32_e32 v232, 0, v116
	v_exp_f32_e32 v159, v161
	v_exp_f32_e32 v161, v165
	v_max_f32_e32 v229, 0, v106
	v_mul_f32_e64 v223, |v108|, s51
	v_add_f32_e32 v141, 1.0, v141
	v_max_f32_e32 v236, 0, v118
	v_exp_f32_e32 v167, v223
	v_log_f32_e32 v242, v141
	v_add_f32_e32 v141, 1.0, v161
	v_add_f32_e32 v132, 1.0, v132
	v_log_f32_e32 v250, v141
	v_mul_f32_e64 v141, |v109|, s51
	v_log_f32_e32 v240, v132
	v_add_f32_e32 v132, 1.0, v159
	v_exp_f32_e32 v141, v141
	v_log_f32_e32 v248, v132
	v_max_f32_e32 v233, 0, v108
	v_add_f32_e32 v132, 1.0, v167
	v_log_f32_e32 v249, v132
	v_max_f32_e32 v235, 0, v109
	v_add_f32_e32 v132, 1.0, v141
	v_mul_f32_e64 v141, |v110|, s51
	v_add_co_u32_e32 v98, vcc, s0, v176
	v_exp_f32_e32 v141, v141
	s_nop 0
	v_addc_co_u32_e32 v99, vcc, 0, v177, vcc
	global_load_dwordx2 v[100:101], v[176:177], off
	global_load_dwordx2 v[102:103], v[176:177], off offset:32
	global_load_dwordx2 v[96:97], v[98:99], off
	s_nop 0
	global_load_dwordx2 v[98:99], v[98:99], off offset:32
	v_mul_f32_e64 v157, |v115|, s51
	v_mul_f32_e64 v169, |v106|, s51
	v_mul_f32_e64 v179, |v107|, s51
	v_max_f32_e32 v230, 0, v115
	v_exp_f32_e32 v149, v157
	v_exp_f32_e32 v155, v169
	v_exp_f32_e32 v157, v179
	v_log_f32_e32 v251, v132
	v_max_f32_e32 v227, 0, v105
	v_mul_f32_e64 v169, |v118|, s51
	v_mul_f32_e64 v179, |v119|, s51
	v_max_f32_e32 v237, 0, v110
	v_add_f32_e32 v132, 1.0, v141
	v_mul_f32_e64 v141, |v111|, s51
	v_max_f32_e32 v234, 0, v117
	v_exp_f32_e32 v163, v169
	v_exp_f32_e32 v165, v179
	v_exp_f32_e32 v141, v141
	v_add_f32_e32 v143, 1.0, v143
	v_add_f32_e32 v149, 1.0, v149
	v_add_f32_e32 v155, 1.0, v155
	v_add_f32_e32 v157, 1.0, v157
	v_max_f32_e32 v178, v107, v107
	v_add_f32_e32 v153, 1.0, v153
	v_log_f32_e32 v244, v143
	v_log_f32_e32 v246, v149
	v_log_f32_e32 v245, v155
	v_log_f32_e32 v247, v157
	v_log_f32_e32 v253, v132
	v_max_f32_e32 v231, 0, v178
	v_add_f32_e32 v151, 1.0, v151
	v_log_f32_e32 v243, v153
	v_add_f32_e32 v143, 1.0, v163
	v_add_f32_e32 v149, 1.0, v165
	v_max_f32_e32 v239, 0, v111
	v_add_f32_e32 v132, 1.0, v141
	v_max_f32_e32 v238, 0, v119
	v_log_f32_e32 v241, v151
	v_log_f32_e32 v252, v143
	v_log_f32_e32 v178, v149
	v_log_f32_e32 v179, v132
	v_pk_fma_f32 v[228:229], v[244:245], s[62:63], v[228:229] op_sel_hi:[1,0,1]
	v_pk_fma_f32 v[230:231], v[246:247], s[62:63], v[230:231] op_sel_hi:[1,0,1]
	v_pk_fma_f32 v[226:227], v[242:243], s[62:63], v[226:227] op_sel_hi:[1,0,1]
	v_pk_add_f32 v[228:229], v[228:229], v[230:231] neg_lo:[1,1] neg_hi:[1,1]
	v_pk_fma_f32 v[224:225], v[240:241], s[62:63], v[224:225] op_sel_hi:[1,0,1]
	v_pk_fma_f32 v[236:237], v[252:253], s[62:63], v[236:237] op_sel_hi:[1,0,1]
	v_pk_fma_f32 v[178:179], v[178:179], s[62:63], v[238:239] op_sel_hi:[1,0,1]
	v_pk_add_f32 v[226:227], v[228:229], v[226:227] neg_lo:[0,1] neg_hi:[0,1]
	v_pk_fma_f32 v[234:235], v[250:251], s[62:63], v[234:235] op_sel_hi:[1,0,1]
	v_pk_add_f32 v[224:225], v[226:227], v[224:225] neg_lo:[0,1] neg_hi:[0,1]
	v_pk_add_f32 v[236:237], v[236:237], v[178:179] neg_lo:[1,1] neg_hi:[1,1]
	v_pk_fma_f32 v[232:233], v[248:249], s[62:63], v[232:233] op_sel_hi:[1,0,1]
	v_pk_add_f32 v[234:235], v[236:237], v[234:235] neg_lo:[0,1] neg_hi:[0,1]
	v_mov_b32_e32 v132, v224
	v_mov_b32_e32 v141, v224
	v_mov_b32_e32 v143, v225
	v_mov_b32_e32 v149, v225
	v_pk_add_f32 v[232:233], v[234:235], v[232:233] neg_lo:[0,1] neg_hi:[0,1]
	v_permlane16_swap_b32_e32 v132, v141
	v_permlane16_swap_b32_e32 v143, v149
	v_cndmask_b32_e64 v239, v143, v149, s[8:9]
	v_cndmask_b32_e64 v238, v132, v141, s[8:9]
	v_mov_b32_e32 v132, v232
	v_mov_b32_e32 v141, v232
	v_mov_b32_e32 v143, v233
	v_mov_b32_e32 v149, v233
	v_pk_add_f32 v[238:239], v[224:225], v[238:239]
	v_permlane16_swap_b32_e32 v132, v141
	v_permlane16_swap_b32_e32 v143, v149
	v_cndmask_b32_e64 v241, v143, v149, s[8:9]
	v_cndmask_b32_e64 v240, v132, v141, s[8:9]
	v_mov_b32_e32 v132, v238
	v_mov_b32_e32 v141, v238
	v_mov_b32_e32 v143, v239
	v_mov_b32_e32 v149, v239
	v_pk_add_f32 v[240:241], v[232:233], v[240:241]
	v_permlane32_swap_b32_e32 v132, v141
	v_permlane32_swap_b32_e32 v143, v149
	v_cndmask_b32_e64 v243, v143, v149, s[6:7]
	v_cndmask_b32_e64 v242, v132, v141, s[6:7]
	v_mov_b32_e32 v132, v240
	v_mov_b32_e32 v141, v240
	v_mov_b32_e32 v143, v241
	v_mov_b32_e32 v149, v241
	v_permlane32_swap_b32_e32 v132, v141
	s_nop 0
	v_permlane32_swap_b32_e32 v143, v149
	v_cndmask_b32_e64 v245, v143, v149, s[6:7]
	v_cndmask_b32_e64 v244, v132, v141, s[6:7]
	v_pk_add_f32 v[246:247], v[240:241], v[232:233] neg_lo:[0,1] neg_hi:[0,1]
	v_pk_add_f32 v[240:241], v[240:241], v[244:245]
	v_pk_add_f32 v[250:251], v[238:239], v[224:225] neg_lo:[0,1] neg_hi:[0,1]
	v_pk_add_f32 v[248:249], v[170:171], v[240:241]
	v_fma_f32 v132, v208, v246, v170
	v_fma_f32 v141, v208, v250, v248
	v_fmac_f32_e32 v141, v209, v242
	v_add_f32_e32 v112, v112, v141
	v_add_f32_e32 v112, v224, v112
	v_fmac_f32_e32 v132, v209, v244
	v_mul_f32_e32 v112, 0x3fb8aa3b, v112
	v_exp_f32_e32 v143, v112
	v_add_f32_e32 v112, v117, v132
	v_add_f32_e32 v112, v234, v112
	v_mul_f32_e32 v112, 0x3fb8aa3b, v112
	v_exp_f32_e32 v117, v112
	v_add_f32_e32 v112, v113, v141
	v_add_f32_e32 v112, v226, v112
	v_mul_f32_e32 v112, 0x3fb8aa3b, v112
	v_exp_f32_e32 v149, v112
	v_add_f32_e32 v112, v118, v132
	v_add_f32_e32 v112, v236, v112
	v_mul_f32_e32 v112, 0x3fb8aa3b, v112
	v_exp_f32_e32 v118, v112
	v_add_f32_e32 v112, v114, v141
	v_add_f32_e32 v112, v228, v112
	v_mul_f32_e32 v112, 0x3fb8aa3b, v112
	v_exp_f32_e32 v114, v112
	v_add_f32_e32 v112, v119, v132
	v_sub_f32_e32 v112, v112, v178
	v_mul_f32_e32 v112, 0x3fb8aa3b, v112
	v_exp_f32_e32 v119, v112
	v_add_f32_e32 v112, v115, v141
	v_sub_f32_e32 v112, v112, v230
	v_mul_f32_e32 v112, 0x3fb8aa3b, v112
	v_exp_f32_e32 v115, v112
	v_pk_add_f32 v[112:113], v[238:239], v[242:243]
	v_fmac_f32_e32 v249, v208, v251
	v_pk_add_f32 v[112:113], v[112:113], v[240:241]
	v_fmac_f32_e32 v249, v209, v243
	v_pk_add_f32 v[112:113], v[170:171], v[112:113]
	v_fmac_f32_e32 v171, v208, v247
	v_fmac_f32_e32 v171, v209, v245
	v_add_f32_e32 v108, v108, v171
	v_add_f32_e32 v104, v104, v249
	v_add_f32_e32 v108, v233, v108
	v_add_f32_e32 v104, v225, v104
	v_mul_f32_e32 v108, 0x3fb8aa3b, v108
	v_mul_f32_e32 v104, 0x3fb8aa3b, v104
	v_add_f32_e32 v116, v116, v132
	v_exp_f32_e32 v132, v108
	v_exp_f32_e32 v108, v104
	v_add_f32_e32 v104, v109, v171
	v_add_f32_e32 v104, v235, v104
	v_mul_f32_e32 v104, 0x3fb8aa3b, v104
	v_exp_f32_e32 v141, v104
	v_add_f32_e32 v104, v105, v249
	v_add_f32_e32 v104, v227, v104
	v_mul_f32_e32 v104, 0x3fb8aa3b, v104
	v_exp_f32_e32 v109, v104
	v_add_f32_e32 v104, v110, v171
	v_add_f32_e32 v104, v237, v104
	v_mul_f32_e32 v104, 0x3fb8aa3b, v104
	v_exp_f32_e32 v151, v104
	v_add_f32_e32 v104, v106, v249
	v_add_f32_e32 v104, v229, v104
	v_mul_f32_e32 v104, 0x3fb8aa3b, v104
	v_exp_f32_e32 v110, v104
	v_add_f32_e32 v104, v111, v171
	v_sub_f32_e32 v104, v104, v179
	v_mul_f32_e32 v104, 0x3fb8aa3b, v104
	v_exp_f32_e32 v111, v104
	v_add_f32_e32 v104, v107, v249
	v_add_f32_e32 v116, v232, v116
	v_sub_f32_e32 v104, v104, v231
	v_mul_f32_e32 v116, 0x3fb8aa3b, v116
	v_mul_f32_e32 v104, 0x3fb8aa3b, v104
	v_exp_f32_e32 v116, v116
	v_exp_f32_e32 v153, v104
	v_cvt_pk_bf16_f32 v104, v143, v149
	v_cvt_pk_bf16_f32 v105, v114, v115
	v_cvt_pk_bf16_f32 v106, v116, v117
	v_cvt_pk_bf16_f32 v107, v118, v119
	v_cvt_pk_bf16_f32 v108, v108, v109
	v_cvt_pk_bf16_f32 v109, v110, v153
	v_cvt_pk_bf16_f32 v110, v132, v141
	v_cvt_pk_bf16_f32 v111, v151, v111
	s_mov_b32 s0, 0x40000
	s_waitcnt vmcnt(2)
	v_mfma_f32_16x16x32_bf16 v[92:95], v[100:103], v[104:107], v[92:95]
	v_mov_b64_e32 v[170:171], v[112:113]
	v_mfma_f32_16x16x32_bf16 v[76:79], v[100:103], v[108:111], v[76:79]
	v_add_co_u32_e32 v102, vcc, s0, v176
	s_mov_b32 s0, 0x60000
	s_nop 0
	v_addc_co_u32_e32 v103, vcc, 0, v177, vcc
	v_add_co_u32_e32 v114, vcc, s0, v176
	global_load_dwordx2 v[100:101], v[102:103], off
	s_nop 0
	global_load_dwordx2 v[102:103], v[102:103], off offset:32
	v_addc_co_u32_e32 v115, vcc, 0, v177, vcc
	s_waitcnt vmcnt(2)
	v_mfma_f32_16x16x32_bf16 v[88:91], v[96:99], v[104:107], v[88:91]
	v_cmp_gt_f32_e32 vcc, s63, v112
	v_cmp_gt_f32_e64 s[0:1], s63, v113
	s_and_b64 s[0:1], vcc, s[0:1]
	v_mfma_f32_16x16x32_bf16 v[72:75], v[96:99], v[108:111], v[72:75]
	global_load_dwordx2 v[96:97], v[114:115], off
	global_load_dwordx2 v[98:99], v[114:115], off offset:32
	s_waitcnt vmcnt(2)
	v_mfma_f32_16x16x32_bf16 v[84:87], v[100:103], v[104:107], v[84:87]
	v_mfma_f32_16x16x32_bf16 v[68:71], v[100:103], v[108:111], v[68:71]
	s_waitcnt vmcnt(0)
	v_mfma_f32_16x16x32_bf16 v[80:83], v[96:99], v[104:107], v[80:83]
	v_mfma_f32_16x16x32_bf16 v[64:67], v[96:99], v[108:111], v[64:67]
	v_cndmask_b32_e64 v96, 0, 1, s[0:1]
	v_cmp_ne_u32_e32 vcc, 0, v96
	s_cmp_eq_u64 vcc, exec
	s_cselect_b64 s[0:1], -1, 0
	s_sub_i32 s54, s54, 32
	s_andn2_b64 vcc, exec, s[0:1]
	s_cbranch_vccz .LBB0_208
